# v27: w_in epilogue V-tile: 128 global_store_short per wave -> 64 global_store_dword (lane-pair exchange via DPP quad_perm + v_perm_b32, same bytes written)
# baseline (speedup 1.0000x reference)
; __device__ __forceinline__ bf16_t f2bf1(float f) { return (bf16_t)(cvt_pk_bf16(f, 0.f) & 0xffffu); }
;     __device__ __forceinline__ void operator()(const f32x4 (&acc)[2][2][4][2], const Unit& u, int wr, int wc, int fr, int fq) const {
;     ...
;         } else if (pn == 2) {
;             bf16_t* VTG = (bf16_t*)(ws + WS_VTG);
;             float* ovp = out + O_WVP + (size_t)l * 131072; float* ovs = out + O_WVS + (size_t)l * 524288;
; #pragma unroll
;             for (int ai = 0; ai < 2; ++ai)
; #pragma unroll
;                 for (int m = 0; m < 4; ++m) {
;                     int row = u.pm * BM + ai * HALF + wr * 64 + m * 16 + fr;
;                     asm volatile("" : "+v"(row));
;                     const float rs = R[ai * HALF + wr * 64 + m * 16 + fr];
;                     const int sb = (row - E_MP) >> 6, st = (row - E_MP) & 63, pb = row >> 11, pt = row & 2047;
; #pragma unroll
;                     for (int bj = 0; bj < 2; ++bj) {
;                         const f32x4 v0 = acc[ai][bj][m][0] * rs, v1 = acc[ai][bj][m][1] * rs;
;                         const int c0 = (wc - 2) * 64 + bj * 32 + 8 * fq;
;                         bf16_t* vp = VTG + (size_t)c0 * E_MT + row;
; #pragma unroll
;                         for (int j = 0; j < 4; ++j) { vp[(size_t)j * E_MT] = f2bf1(v0[j]); vp[(size_t)(4 + j) * E_MT] = f2bf1(v1[j]); }
;                         if (is_s) { float* d = ovs + ((size_t)(sb * 128 + 64 + st) * 128 + c0); __builtin_nontemporal_store(v0, (f32x4*)d); __builtin_nontemporal_store(v1, (f32x4*)(d + 4)); }
;                         else if (pt >= 1920) { float* d = ovp + ((size_t)(pb * 128 + (pt - 1920)) * 128 + c0); __builtin_nontemporal_store(v0, (f32x4*)d); __builtin_nontemporal_store(v1, (f32x4*)(d + 4)); }
;                     }
.LBB0_626:
	s_andn2_b64 vcc, exec, s[0:1]
	s_cbranch_vccnz .LBB0_660
	v_and_b32_e32 v223, 1, v222
	v_cmp_eq_u32_e32 vcc, 1, v223
	v_mov_b32_e32 v220, 0x5040100
	v_mov_b32_e32 v250, 0x3020706
	s_mov_b32 s101, 0
	v_cndmask_b32_e32 v220, v220, v250, vcc
	v_mov_b32_e32 v250, 0x8ffe
	v_cndmask_b32_e32 v223, v185, v250, vcc
	v_lshl_add_u32 v170, s53, 8, v153
	v_mov_b32_e32 v128, v170
	s_movk_i32 s0, 0x77f
	v_ashrrev_i32_e32 v129, 31, v128
	v_lshl_add_u64 v[138:139], v[128:129], 1, s[42:43]
	v_ashrrev_i32_e32 v129, 4, v128
	v_and_b32_e32 v130, 0x7ff, v128
	v_and_b32_e32 v129, 0xffffff80, v129
	s_movk_i32 s4, 0xf880
	ds_read_b32 v136, v165
	v_and_b32_e32 v132, 63, v128
	v_cmp_lt_u32_e64 s[0:1], s0, v130
	v_add3_u32 v130, v130, v129, s4
	v_lshlrev_b32_e32 v128, 1, v128
	s_movk_i32 s4, 0xff80
	v_and_or_b32 v128, v128, s4, v132
	v_add_u32_e32 v128, 0xffff8040, v128
	v_ashrrev_i32_e32 v131, 31, v130
	v_ashrrev_i32_e32 v129, 31, v128
	v_lshl_add_u64 v[172:173], v[138:139], 0, v[156:157]
	s_mov_b32 s4, 0x24000
	v_lshlrev_b64 v[130:131], 9, v[130:131]
	v_lshlrev_b64 v[128:129], 9, v[128:129]
	v_lshl_add_u64 v[140:141], s[26:27], 0, v[130:131]
	v_lshl_add_u64 v[142:143], s[30:31], 0, v[128:129]
	s_waitcnt lgkmcnt(0)
	v_pk_mul_f32 v[130:131], v[126:127], v[136:137] op_sel_hi:[1,0]
	v_pk_mul_f32 v[128:129], v[124:125], v[136:137] op_sel_hi:[1,0]
	v_pk_mul_f32 v[134:135], v[122:123], v[136:137] op_sel_hi:[1,0]
	v_pk_mul_f32 v[132:133], v[120:121], v[136:137] op_sel_hi:[1,0]
	s_mov_b32 s4, 0x9000
	s_mov_b32 s4, 0x2d000
	s_nop 0
	s_mov_b32 s4, 0x12000
	s_nop 0
	s_mov_b32 s4, 0x36000
	s_nop 0
	s_or_b64 s[0:1], s[38:39], s[0:1]
	s_nop 0
	v_cndmask_b32_e64 v141, v141, v143, s[38:39]
	s_nop 0
	v_cndmask_b32_e64 v140, v140, v142, s[38:39]
	s_nop 0
	v_lshlrev_b32_e32 v184, 2, v154
	v_cvt_pk_bf16_f32 v190, v128, v129
	v_cvt_pk_bf16_f32 v191, v130, v131
	v_cvt_pk_bf16_f32 v217, v132, v133
	v_cvt_pk_bf16_f32 v226, v134, v135
	v_add_co_u32_e32 v172, vcc, v223, v172
	s_nop 1
	v_addc_co_u32_e32 v173, vcc, 0, v173, vcc
	v_mov_b32_dpp v250, v190 quad_perm:[1,0,3,2] row_mask:0xf bank_mask:0xf
	v_perm_b32 v190, v250, v190, v220
	global_store_dword v[172:173], v190, off
	s_mov_b32 s100, 0x12000
	v_lshl_add_u64 v[174:175], v[172:173], 0, s[100:101]
	v_mov_b32_dpp v250, v191 quad_perm:[1,0,3,2] row_mask:0xf bank_mask:0xf
	v_perm_b32 v191, v250, v191, v220
	global_store_dword v[174:175], v191, off
	s_mov_b32 s100, 0x24000
	v_lshl_add_u64 v[174:175], v[172:173], 0, s[100:101]
	v_mov_b32_dpp v250, v217 quad_perm:[1,0,3,2] row_mask:0xf bank_mask:0xf
	v_perm_b32 v217, v250, v217, v220
	global_store_dword v[174:175], v217, off
	s_mov_b32 s100, 0x36000
	v_lshl_add_u64 v[174:175], v[172:173], 0, s[100:101]
	v_mov_b32_dpp v250, v226 quad_perm:[1,0,3,2] row_mask:0xf bank_mask:0xf
	v_perm_b32 v226, v250, v226, v220
	global_store_dword v[174:175], v226, off
	s_and_saveexec_b64 s[4:5], s[0:1]
	s_cbranch_execz .LBB0_629
	v_lshl_add_u64 v[142:143], v[140:141], 0, v[184:185]
	global_store_dwordx4 v[142:143], v[128:131], off offset:-512 nt
	global_store_dwordx4 v[142:143], v[132:135], off offset:-496 nt
.LBB0_629:
	s_or_b64 exec, exec, s[4:5]
	v_mov_b32_e32 v137, v136
	v_mov_b32_e32 v132, v136
	v_mov_b32_e32 v133, v136
	v_pk_mul_f32 v[130:131], v[118:119], v[132:133]
	v_pk_mul_f32 v[128:129], v[116:117], v[136:137]
	v_pk_mul_f32 v[134:135], v[114:115], v[132:133]
	v_pk_mul_f32 v[132:133], v[112:113], v[136:137]
	v_lshl_add_u64 v[136:137], v[138:139], 0, v[158:159]
	s_mov_b32 s4, 0x24000
	s_mov_b32 s4, 0x9000
	s_nop 0
	s_mov_b32 s4, 0x2d000
	s_nop 0
	s_mov_b32 s4, 0x12000
	s_nop 0
	s_mov_b32 s4, 0x36000
	s_nop 0
	s_nop 1
	s_nop 1
	s_nop 0
	v_cvt_pk_bf16_f32 v190, v128, v129
	v_cvt_pk_bf16_f32 v191, v130, v131
	v_cvt_pk_bf16_f32 v217, v132, v133
	v_cvt_pk_bf16_f32 v226, v134, v135
	v_add_co_u32_e32 v136, vcc, v223, v136
	s_nop 1
	v_addc_co_u32_e32 v137, vcc, 0, v137, vcc
	v_mov_b32_dpp v250, v190 quad_perm:[1,0,3,2] row_mask:0xf bank_mask:0xf
	v_perm_b32 v190, v250, v190, v220
	global_store_dword v[136:137], v190, off
	s_mov_b32 s100, 0x12000
	v_lshl_add_u64 v[138:139], v[136:137], 0, s[100:101]
	v_mov_b32_dpp v250, v191 quad_perm:[1,0,3,2] row_mask:0xf bank_mask:0xf
	v_perm_b32 v191, v250, v191, v220
	global_store_dword v[138:139], v191, off
	s_mov_b32 s100, 0x24000
	v_lshl_add_u64 v[138:139], v[136:137], 0, s[100:101]
	v_mov_b32_dpp v250, v217 quad_perm:[1,0,3,2] row_mask:0xf bank_mask:0xf
	v_perm_b32 v217, v250, v217, v220
	global_store_dword v[138:139], v217, off
	s_mov_b32 s100, 0x36000
	v_lshl_add_u64 v[138:139], v[136:137], 0, s[100:101]
	v_mov_b32_dpp v250, v226 quad_perm:[1,0,3,2] row_mask:0xf bank_mask:0xf
	v_perm_b32 v226, v250, v226, v220
	global_store_dword v[138:139], v226, off
	v_lshlrev_b32_e32 v136, 2, v164
	s_and_saveexec_b64 s[4:5], s[0:1]
	s_cbranch_execz .LBB0_631
	v_mov_b32_e32 v137, v185
	v_lshl_add_u64 v[138:139], v[140:141], 0, v[136:137]
	global_store_dwordx4 v[138:139], v[128:131], off offset:-512 nt
	global_store_dwordx4 v[138:139], v[132:135], off offset:-496 nt
; __device__ __forceinline__ bf16_t f2bf1(float f) { return (bf16_t)(cvt_pk_bf16(f, 0.f) & 0xffffu); }
;     __device__ __forceinline__ void operator()(const f32x4 (&acc)[2][2][4][2], const Unit& u, int wr, int wc, int fr, int fq) const {
;     ...
;             for (int ai = 0; ai < 2; ++ai)
; #pragma unroll
;                 for (int m = 0; m < 4; ++m) {
;                     int row = u.pm * BM + ai * HALF + wr * 64 + m * 16 + fr;
;                     asm volatile("" : "+v"(row));
;                     const float rs = R[ai * HALF + wr * 64 + m * 16 + fr];
;                     const int sb = (row - E_MP) >> 6, st = (row - E_MP) & 63, pb = row >> 11, pt = row & 2047;
; #pragma unroll
;                     for (int bj = 0; bj < 2; ++bj) {
;                         const f32x4 v0 = acc[ai][bj][m][0] * rs, v1 = acc[ai][bj][m][1] * rs;
;                         const int c0 = (wc - 2) * 64 + bj * 32 + 8 * fq;
;                         bf16_t* vp = VTG + (size_t)c0 * E_MT + row;
; #pragma unroll
;                         for (int j = 0; j < 4; ++j) { vp[(size_t)j * E_MT] = f2bf1(v0[j]); vp[(size_t)(4 + j) * E_MT] = f2bf1(v1[j]); }
;                         if (is_s) { float* d = ovs + ((size_t)(sb * 128 + 64 + st) * 128 + c0); __builtin_nontemporal_store(v0, (f32x4*)d); __builtin_nontemporal_store(v1, (f32x4*)(d + 4)); }
;                         else if (pt >= 1920) { float* d = ovp + ((size_t)(pb * 128 + (pt - 1920)) * 128 + c0); __builtin_nontemporal_store(v0, (f32x4*)d); __builtin_nontemporal_store(v1, (f32x4*)(d + 4)); }
;                     }
.LBB0_631:
	s_or_b64 exec, exec, s[4:5]
	v_or_b32_e32 v128, 16, v170
	s_movk_i32 s0, 0x77f
	v_ashrrev_i32_e32 v129, 31, v128
	v_lshl_add_u64 v[140:141], v[128:129], 1, s[42:43]
	v_ashrrev_i32_e32 v129, 4, v128
	v_and_b32_e32 v130, 0x7ff, v128
	v_and_b32_e32 v129, 0xffffff80, v129
	s_movk_i32 s4, 0xf880
	ds_read_b32 v138, v165 offset:64
	v_and_b32_e32 v132, 63, v128
	v_cmp_lt_u32_e64 s[0:1], s0, v130
	v_add3_u32 v130, v130, v129, s4
	v_lshlrev_b32_e32 v128, 1, v128
	s_movk_i32 s4, 0xff80
	v_and_or_b32 v128, v128, s4, v132
	v_add_u32_e32 v128, 0xffff8040, v128
	v_ashrrev_i32_e32 v129, 31, v128
	v_lshl_add_u64 v[174:175], v[140:141], 0, v[156:157]
	s_mov_b32 s4, 0x24000
	v_lshlrev_b64 v[128:129], 9, v[128:129]
	v_lshl_add_u64 v[172:173], s[30:31], 0, v[128:129]
	s_waitcnt lgkmcnt(0)
	v_pk_mul_f32 v[128:129], v[108:109], v[138:139] op_sel_hi:[1,0]
	s_mov_b32 s4, 0x9000
	v_pk_mul_f32 v[132:133], v[104:105], v[138:139] op_sel_hi:[1,0]
	s_mov_b32 s4, 0x2d000
	s_nop 0
	s_mov_b32 s4, 0x12000
	s_nop 0
	v_ashrrev_i32_e32 v131, 31, v130
	v_lshlrev_b64 v[130:131], 9, v[130:131]
	s_nop 0
	s_mov_b32 s4, 0x36000
	v_lshl_add_u64 v[142:143], s[26:27], 0, v[130:131]
	v_pk_mul_f32 v[130:131], v[110:111], v[138:139] op_sel_hi:[1,0]
	v_pk_mul_f32 v[134:135], v[106:107], v[138:139] op_sel_hi:[1,0]
	s_or_b64 s[0:1], s[38:39], s[0:1]
	s_nop 0
	v_cndmask_b32_e64 v143, v143, v173, s[38:39]
	s_nop 0
	v_cndmask_b32_e64 v142, v142, v172, s[38:39]
	s_nop 0
	v_cvt_pk_bf16_f32 v190, v128, v129
	v_cvt_pk_bf16_f32 v191, v130, v131
	v_cvt_pk_bf16_f32 v217, v132, v133
	v_cvt_pk_bf16_f32 v226, v134, v135
	v_add_co_u32_e32 v174, vcc, v223, v174
	s_nop 1
	v_addc_co_u32_e32 v175, vcc, 0, v175, vcc
	v_mov_b32_dpp v250, v190 quad_perm:[1,0,3,2] row_mask:0xf bank_mask:0xf
	v_perm_b32 v190, v250, v190, v220
	global_store_dword v[174:175], v190, off
	s_mov_b32 s100, 0x12000
	v_lshl_add_u64 v[176:177], v[174:175], 0, s[100:101]
	v_mov_b32_dpp v250, v191 quad_perm:[1,0,3,2] row_mask:0xf bank_mask:0xf
	v_perm_b32 v191, v250, v191, v220
	global_store_dword v[176:177], v191, off
	s_mov_b32 s100, 0x24000
	v_lshl_add_u64 v[176:177], v[174:175], 0, s[100:101]
	v_mov_b32_dpp v250, v217 quad_perm:[1,0,3,2] row_mask:0xf bank_mask:0xf
	v_perm_b32 v217, v250, v217, v220
	global_store_dword v[176:177], v217, off
	s_mov_b32 s100, 0x36000
	v_lshl_add_u64 v[176:177], v[174:175], 0, s[100:101]
	v_mov_b32_dpp v250, v226 quad_perm:[1,0,3,2] row_mask:0xf bank_mask:0xf
	v_perm_b32 v226, v250, v226, v220
	global_store_dword v[176:177], v226, off
	s_and_saveexec_b64 s[4:5], s[0:1]
	s_cbranch_execz .LBB0_633
	v_lshl_add_u64 v[172:173], v[142:143], 0, v[184:185]
	global_store_dwordx4 v[172:173], v[128:131], off offset:-512 nt
	global_store_dwordx4 v[172:173], v[132:135], off offset:-496 nt
.LBB0_633:
	s_or_b64 exec, exec, s[4:5]
	v_mov_b32_e32 v139, v138
	v_mov_b32_e32 v132, v138
	v_mov_b32_e32 v133, v138
	v_pk_mul_f32 v[130:131], v[102:103], v[132:133]
	v_pk_mul_f32 v[128:129], v[100:101], v[138:139]
	v_pk_mul_f32 v[134:135], v[98:99], v[132:133]
	v_pk_mul_f32 v[132:133], v[96:97], v[138:139]
	v_lshl_add_u64 v[138:139], v[140:141], 0, v[158:159]
	s_mov_b32 s4, 0x24000
	s_mov_b32 s4, 0x9000
	s_nop 0
	s_mov_b32 s4, 0x2d000
	s_nop 0
	s_mov_b32 s4, 0x12000
	s_nop 0
	s_mov_b32 s4, 0x36000
	s_nop 0
	s_nop 1
	s_nop 1
	s_nop 0
	v_cvt_pk_bf16_f32 v190, v128, v129
	v_cvt_pk_bf16_f32 v191, v130, v131
	v_cvt_pk_bf16_f32 v217, v132, v133
	v_cvt_pk_bf16_f32 v226, v134, v135
	v_add_co_u32_e32 v138, vcc, v223, v138
	s_nop 1
	v_addc_co_u32_e32 v139, vcc, 0, v139, vcc
	v_mov_b32_dpp v250, v190 quad_perm:[1,0,3,2] row_mask:0xf bank_mask:0xf
	v_perm_b32 v190, v250, v190, v220
	global_store_dword v[138:139], v190, off
	s_mov_b32 s100, 0x12000
	v_lshl_add_u64 v[140:141], v[138:139], 0, s[100:101]
	v_mov_b32_dpp v250, v191 quad_perm:[1,0,3,2] row_mask:0xf bank_mask:0xf
	v_perm_b32 v191, v250, v191, v220
	global_store_dword v[140:141], v191, off
	s_mov_b32 s100, 0x24000
	v_lshl_add_u64 v[140:141], v[138:139], 0, s[100:101]
	v_mov_b32_dpp v250, v217 quad_perm:[1,0,3,2] row_mask:0xf bank_mask:0xf
	v_perm_b32 v217, v250, v217, v220
	global_store_dword v[140:141], v217, off
	s_mov_b32 s100, 0x36000
	v_lshl_add_u64 v[140:141], v[138:139], 0, s[100:101]
	v_mov_b32_dpp v250, v226 quad_perm:[1,0,3,2] row_mask:0xf bank_mask:0xf
	v_perm_b32 v226, v250, v226, v220
	global_store_dword v[140:141], v226, off
	s_and_saveexec_b64 s[4:5], s[0:1]
	s_cbranch_execz .LBB0_635
	v_mov_b32_e32 v137, v185
	v_lshl_add_u64 v[138:139], v[142:143], 0, v[136:137]
	global_store_dwordx4 v[138:139], v[128:131], off offset:-512 nt
	global_store_dwordx4 v[138:139], v[132:135], off offset:-496 nt
; __device__ __forceinline__ bf16_t f2bf1(float f) { return (bf16_t)(cvt_pk_bf16(f, 0.f) & 0xffffu); }
;     __device__ __forceinline__ void operator()(const f32x4 (&acc)[2][2][4][2], const Unit& u, int wr, int wc, int fr, int fq) const {
;     ...
;             for (int ai = 0; ai < 2; ++ai)
; #pragma unroll
;                 for (int m = 0; m < 4; ++m) {
;                     int row = u.pm * BM + ai * HALF + wr * 64 + m * 16 + fr;
;                     asm volatile("" : "+v"(row));
;                     const float rs = R[ai * HALF + wr * 64 + m * 16 + fr];
;                     const int sb = (row - E_MP) >> 6, st = (row - E_MP) & 63, pb = row >> 11, pt = row & 2047;
; #pragma unroll
;                     for (int bj = 0; bj < 2; ++bj) {
;                         const f32x4 v0 = acc[ai][bj][m][0] * rs, v1 = acc[ai][bj][m][1] * rs;
;                         const int c0 = (wc - 2) * 64 + bj * 32 + 8 * fq;
;                         bf16_t* vp = VTG + (size_t)c0 * E_MT + row;
; #pragma unroll
;                         for (int j = 0; j < 4; ++j) { vp[(size_t)j * E_MT] = f2bf1(v0[j]); vp[(size_t)(4 + j) * E_MT] = f2bf1(v1[j]); }
;                         if (is_s) { float* d = ovs + ((size_t)(sb * 128 + 64 + st) * 128 + c0); __builtin_nontemporal_store(v0, (f32x4*)d); __builtin_nontemporal_store(v1, (f32x4*)(d + 4)); }
;                         else if (pt >= 1920) { float* d = ovp + ((size_t)(pb * 128 + (pt - 1920)) * 128 + c0); __builtin_nontemporal_store(v0, (f32x4*)d); __builtin_nontemporal_store(v1, (f32x4*)(d + 4)); }
;                     }
.LBB0_635:
	s_or_b64 exec, exec, s[4:5]
	v_or_b32_e32 v128, 32, v170
	s_movk_i32 s0, 0x77f
	v_ashrrev_i32_e32 v129, 31, v128
	v_lshl_add_u64 v[140:141], v[128:129], 1, s[42:43]
	v_ashrrev_i32_e32 v129, 4, v128
	v_and_b32_e32 v130, 0x7ff, v128
	v_and_b32_e32 v129, 0xffffff80, v129
	s_movk_i32 s4, 0xf880
	ds_read_b32 v138, v165 offset:128
	v_and_b32_e32 v132, 63, v128
	v_cmp_lt_u32_e64 s[0:1], s0, v130
	v_add3_u32 v130, v130, v129, s4
	v_lshlrev_b32_e32 v128, 1, v128
	s_movk_i32 s4, 0xff80
	v_and_or_b32 v128, v128, s4, v132
	v_add_u32_e32 v128, 0xffff8040, v128
	v_ashrrev_i32_e32 v129, 31, v128
	v_lshl_add_u64 v[174:175], v[140:141], 0, v[156:157]
	s_mov_b32 s4, 0x24000
	v_lshlrev_b64 v[128:129], 9, v[128:129]
	v_lshl_add_u64 v[172:173], s[30:31], 0, v[128:129]
	s_waitcnt lgkmcnt(0)
	v_pk_mul_f32 v[128:129], v[92:93], v[138:139] op_sel_hi:[1,0]
	s_mov_b32 s4, 0x9000
	v_pk_mul_f32 v[132:133], v[88:89], v[138:139] op_sel_hi:[1,0]
	s_mov_b32 s4, 0x2d000
	s_nop 0
	s_mov_b32 s4, 0x12000
	s_nop 0
	v_ashrrev_i32_e32 v131, 31, v130
	v_lshlrev_b64 v[130:131], 9, v[130:131]
	s_nop 0
	s_mov_b32 s4, 0x36000
	v_lshl_add_u64 v[142:143], s[26:27], 0, v[130:131]
	v_pk_mul_f32 v[130:131], v[94:95], v[138:139] op_sel_hi:[1,0]
	v_pk_mul_f32 v[134:135], v[90:91], v[138:139] op_sel_hi:[1,0]
	s_or_b64 s[0:1], s[38:39], s[0:1]
	s_nop 0
	v_cndmask_b32_e64 v143, v143, v173, s[38:39]
	s_nop 0
	v_cndmask_b32_e64 v142, v142, v172, s[38:39]
	s_nop 0
	v_cvt_pk_bf16_f32 v190, v128, v129
	v_cvt_pk_bf16_f32 v191, v130, v131
	v_cvt_pk_bf16_f32 v217, v132, v133
	v_cvt_pk_bf16_f32 v226, v134, v135
	v_add_co_u32_e32 v174, vcc, v223, v174
	s_nop 1
	v_addc_co_u32_e32 v175, vcc, 0, v175, vcc
	v_mov_b32_dpp v250, v190 quad_perm:[1,0,3,2] row_mask:0xf bank_mask:0xf
	v_perm_b32 v190, v250, v190, v220
	global_store_dword v[174:175], v190, off
	s_mov_b32 s100, 0x12000
	v_lshl_add_u64 v[176:177], v[174:175], 0, s[100:101]
	v_mov_b32_dpp v250, v191 quad_perm:[1,0,3,2] row_mask:0xf bank_mask:0xf
	v_perm_b32 v191, v250, v191, v220
	global_store_dword v[176:177], v191, off
	s_mov_b32 s100, 0x24000
	v_lshl_add_u64 v[176:177], v[174:175], 0, s[100:101]
	v_mov_b32_dpp v250, v217 quad_perm:[1,0,3,2] row_mask:0xf bank_mask:0xf
	v_perm_b32 v217, v250, v217, v220
	global_store_dword v[176:177], v217, off
	s_mov_b32 s100, 0x36000
	v_lshl_add_u64 v[176:177], v[174:175], 0, s[100:101]
	v_mov_b32_dpp v250, v226 quad_perm:[1,0,3,2] row_mask:0xf bank_mask:0xf
	v_perm_b32 v226, v250, v226, v220
	global_store_dword v[176:177], v226, off
	s_and_saveexec_b64 s[4:5], s[0:1]
	s_cbranch_execz .LBB0_637
	v_lshl_add_u64 v[172:173], v[142:143], 0, v[184:185]
	global_store_dwordx4 v[172:173], v[128:131], off offset:-512 nt
	global_store_dwordx4 v[172:173], v[132:135], off offset:-496 nt
.LBB0_637:
	s_or_b64 exec, exec, s[4:5]
	v_mov_b32_e32 v139, v138
	v_mov_b32_e32 v132, v138
	v_mov_b32_e32 v133, v138
	v_pk_mul_f32 v[130:131], v[86:87], v[132:133]
	v_pk_mul_f32 v[128:129], v[84:85], v[138:139]
	v_pk_mul_f32 v[134:135], v[82:83], v[132:133]
	v_pk_mul_f32 v[132:133], v[80:81], v[138:139]
	v_lshl_add_u64 v[138:139], v[140:141], 0, v[158:159]
	s_mov_b32 s4, 0x24000
	s_mov_b32 s4, 0x9000
	s_nop 0
	s_mov_b32 s4, 0x2d000
	s_nop 0
	s_mov_b32 s4, 0x12000
	s_nop 0
	s_mov_b32 s4, 0x36000
	s_nop 0
	s_nop 1
	s_nop 1
	s_nop 0
	v_cvt_pk_bf16_f32 v190, v128, v129
	v_cvt_pk_bf16_f32 v191, v130, v131
	v_cvt_pk_bf16_f32 v217, v132, v133
	v_cvt_pk_bf16_f32 v226, v134, v135
	v_add_co_u32_e32 v138, vcc, v223, v138
	s_nop 1
	v_addc_co_u32_e32 v139, vcc, 0, v139, vcc
	v_mov_b32_dpp v250, v190 quad_perm:[1,0,3,2] row_mask:0xf bank_mask:0xf
	v_perm_b32 v190, v250, v190, v220
	global_store_dword v[138:139], v190, off
	s_mov_b32 s100, 0x12000
	v_lshl_add_u64 v[140:141], v[138:139], 0, s[100:101]
	v_mov_b32_dpp v250, v191 quad_perm:[1,0,3,2] row_mask:0xf bank_mask:0xf
	v_perm_b32 v191, v250, v191, v220
	global_store_dword v[140:141], v191, off
	s_mov_b32 s100, 0x24000
	v_lshl_add_u64 v[140:141], v[138:139], 0, s[100:101]
	v_mov_b32_dpp v250, v217 quad_perm:[1,0,3,2] row_mask:0xf bank_mask:0xf
	v_perm_b32 v217, v250, v217, v220
	global_store_dword v[140:141], v217, off
	s_mov_b32 s100, 0x36000
	v_lshl_add_u64 v[140:141], v[138:139], 0, s[100:101]
	v_mov_b32_dpp v250, v226 quad_perm:[1,0,3,2] row_mask:0xf bank_mask:0xf
	v_perm_b32 v226, v250, v226, v220
	global_store_dword v[140:141], v226, off
	s_and_saveexec_b64 s[4:5], s[0:1]
	s_cbranch_execz .LBB0_639
	v_mov_b32_e32 v137, v185
	v_lshl_add_u64 v[138:139], v[142:143], 0, v[136:137]
	global_store_dwordx4 v[138:139], v[128:131], off offset:-512 nt
	global_store_dwordx4 v[138:139], v[132:135], off offset:-496 nt
; __device__ __forceinline__ bf16_t f2bf1(float f) { return (bf16_t)(cvt_pk_bf16(f, 0.f) & 0xffffu); }
;     __device__ __forceinline__ void operator()(const f32x4 (&acc)[2][2][4][2], const Unit& u, int wr, int wc, int fr, int fq) const {
;     ...
;             for (int ai = 0; ai < 2; ++ai)
; #pragma unroll
;                 for (int m = 0; m < 4; ++m) {
;                     int row = u.pm * BM + ai * HALF + wr * 64 + m * 16 + fr;
;                     asm volatile("" : "+v"(row));
;                     const float rs = R[ai * HALF + wr * 64 + m * 16 + fr];
;                     const int sb = (row - E_MP) >> 6, st = (row - E_MP) & 63, pb = row >> 11, pt = row & 2047;
; #pragma unroll
;                     for (int bj = 0; bj < 2; ++bj) {
;                         const f32x4 v0 = acc[ai][bj][m][0] * rs, v1 = acc[ai][bj][m][1] * rs;
;                         const int c0 = (wc - 2) * 64 + bj * 32 + 8 * fq;
;                         bf16_t* vp = VTG + (size_t)c0 * E_MT + row;
; #pragma unroll
;                         for (int j = 0; j < 4; ++j) { vp[(size_t)j * E_MT] = f2bf1(v0[j]); vp[(size_t)(4 + j) * E_MT] = f2bf1(v1[j]); }
;                         if (is_s) { float* d = ovs + ((size_t)(sb * 128 + 64 + st) * 128 + c0); __builtin_nontemporal_store(v0, (f32x4*)d); __builtin_nontemporal_store(v1, (f32x4*)(d + 4)); }
;                         else if (pt >= 1920) { float* d = ovp + ((size_t)(pb * 128 + (pt - 1920)) * 128 + c0); __builtin_nontemporal_store(v0, (f32x4*)d); __builtin_nontemporal_store(v1, (f32x4*)(d + 4)); }
;                     }
.LBB0_639:
	s_or_b64 exec, exec, s[4:5]
	v_or_b32_e32 v128, 48, v170
	s_movk_i32 s0, 0x77f
	v_ashrrev_i32_e32 v129, 31, v128
	v_lshl_add_u64 v[140:141], v[128:129], 1, s[42:43]
	v_ashrrev_i32_e32 v129, 4, v128
	v_and_b32_e32 v130, 0x7ff, v128
	v_and_b32_e32 v129, 0xffffff80, v129
	s_movk_i32 s4, 0xf880
	ds_read_b32 v138, v165 offset:192
	v_and_b32_e32 v132, 63, v128
	v_cmp_lt_u32_e64 s[0:1], s0, v130
	v_add3_u32 v130, v130, v129, s4
	v_lshlrev_b32_e32 v128, 1, v128
	s_movk_i32 s4, 0xff80
	v_and_or_b32 v128, v128, s4, v132
	v_add_u32_e32 v128, 0xffff8040, v128
	v_ashrrev_i32_e32 v129, 31, v128
	v_lshl_add_u64 v[174:175], v[140:141], 0, v[156:157]
	s_mov_b32 s4, 0x24000
	v_lshlrev_b64 v[128:129], 9, v[128:129]
	v_lshl_add_u64 v[172:173], s[30:31], 0, v[128:129]
	s_waitcnt lgkmcnt(0)
	v_pk_mul_f32 v[128:129], v[76:77], v[138:139] op_sel_hi:[1,0]
	s_mov_b32 s4, 0x9000
	v_pk_mul_f32 v[132:133], v[72:73], v[138:139] op_sel_hi:[1,0]
	s_mov_b32 s4, 0x2d000
	s_nop 0
	s_mov_b32 s4, 0x12000
	s_nop 0
	v_ashrrev_i32_e32 v131, 31, v130
	v_lshlrev_b64 v[130:131], 9, v[130:131]
	s_nop 0
	s_mov_b32 s4, 0x36000
	v_lshl_add_u64 v[142:143], s[26:27], 0, v[130:131]
	v_pk_mul_f32 v[130:131], v[78:79], v[138:139] op_sel_hi:[1,0]
	v_pk_mul_f32 v[134:135], v[74:75], v[138:139] op_sel_hi:[1,0]
	s_or_b64 s[0:1], s[38:39], s[0:1]
	s_nop 0
	v_cndmask_b32_e64 v143, v143, v173, s[38:39]
	s_nop 0
	v_cndmask_b32_e64 v142, v142, v172, s[38:39]
	s_nop 0
	v_cvt_pk_bf16_f32 v190, v128, v129
	v_cvt_pk_bf16_f32 v191, v130, v131
	v_cvt_pk_bf16_f32 v217, v132, v133
	v_cvt_pk_bf16_f32 v226, v134, v135
	v_add_co_u32_e32 v174, vcc, v223, v174
	s_nop 1
	v_addc_co_u32_e32 v175, vcc, 0, v175, vcc
	v_mov_b32_dpp v250, v190 quad_perm:[1,0,3,2] row_mask:0xf bank_mask:0xf
	v_perm_b32 v190, v250, v190, v220
	global_store_dword v[174:175], v190, off
	s_mov_b32 s100, 0x12000
	v_lshl_add_u64 v[176:177], v[174:175], 0, s[100:101]
	v_mov_b32_dpp v250, v191 quad_perm:[1,0,3,2] row_mask:0xf bank_mask:0xf
	v_perm_b32 v191, v250, v191, v220
	global_store_dword v[176:177], v191, off
	s_mov_b32 s100, 0x24000
	v_lshl_add_u64 v[176:177], v[174:175], 0, s[100:101]
	v_mov_b32_dpp v250, v217 quad_perm:[1,0,3,2] row_mask:0xf bank_mask:0xf
	v_perm_b32 v217, v250, v217, v220
	global_store_dword v[176:177], v217, off
	s_mov_b32 s100, 0x36000
	v_lshl_add_u64 v[176:177], v[174:175], 0, s[100:101]
	v_mov_b32_dpp v250, v226 quad_perm:[1,0,3,2] row_mask:0xf bank_mask:0xf
	v_perm_b32 v226, v250, v226, v220
	global_store_dword v[176:177], v226, off
	s_and_saveexec_b64 s[4:5], s[0:1]
	s_cbranch_execz .LBB0_641
	v_lshl_add_u64 v[172:173], v[142:143], 0, v[184:185]
	global_store_dwordx4 v[172:173], v[128:131], off offset:-512 nt
	global_store_dwordx4 v[172:173], v[132:135], off offset:-496 nt
.LBB0_641:
	s_or_b64 exec, exec, s[4:5]
	v_mov_b32_e32 v139, v138
	v_mov_b32_e32 v132, v138
	v_mov_b32_e32 v133, v138
	v_pk_mul_f32 v[130:131], v[70:71], v[132:133]
	v_pk_mul_f32 v[128:129], v[68:69], v[138:139]
	v_pk_mul_f32 v[134:135], v[66:67], v[132:133]
	v_pk_mul_f32 v[132:133], v[64:65], v[138:139]
	v_lshl_add_u64 v[138:139], v[140:141], 0, v[158:159]
	s_mov_b32 s4, 0x24000
	s_mov_b32 s4, 0x9000
	s_nop 0
	s_mov_b32 s4, 0x2d000
	s_nop 0
	s_mov_b32 s4, 0x12000
	s_nop 0
	s_mov_b32 s4, 0x36000
	s_nop 0
	s_nop 1
	s_nop 1
	s_nop 0
	v_cvt_pk_bf16_f32 v190, v128, v129
	v_cvt_pk_bf16_f32 v191, v130, v131
	v_cvt_pk_bf16_f32 v217, v132, v133
	v_cvt_pk_bf16_f32 v226, v134, v135
	v_add_co_u32_e32 v138, vcc, v223, v138
	s_nop 1
	v_addc_co_u32_e32 v139, vcc, 0, v139, vcc
	v_mov_b32_dpp v250, v190 quad_perm:[1,0,3,2] row_mask:0xf bank_mask:0xf
	v_perm_b32 v190, v250, v190, v220
	global_store_dword v[138:139], v190, off
	s_mov_b32 s100, 0x12000
	v_lshl_add_u64 v[140:141], v[138:139], 0, s[100:101]
	v_mov_b32_dpp v250, v191 quad_perm:[1,0,3,2] row_mask:0xf bank_mask:0xf
	v_perm_b32 v191, v250, v191, v220
	global_store_dword v[140:141], v191, off
	s_mov_b32 s100, 0x24000
	v_lshl_add_u64 v[140:141], v[138:139], 0, s[100:101]
	v_mov_b32_dpp v250, v217 quad_perm:[1,0,3,2] row_mask:0xf bank_mask:0xf
	v_perm_b32 v217, v250, v217, v220
	global_store_dword v[140:141], v217, off
	s_mov_b32 s100, 0x36000
	v_lshl_add_u64 v[140:141], v[138:139], 0, s[100:101]
	v_mov_b32_dpp v250, v226 quad_perm:[1,0,3,2] row_mask:0xf bank_mask:0xf
	v_perm_b32 v226, v250, v226, v220
	global_store_dword v[140:141], v226, off
	s_and_saveexec_b64 s[4:5], s[0:1]
	s_cbranch_execz .LBB0_643
	v_mov_b32_e32 v137, v185
	v_lshl_add_u64 v[138:139], v[142:143], 0, v[136:137]
	global_store_dwordx4 v[138:139], v[128:131], off offset:-512 nt
	global_store_dwordx4 v[138:139], v[132:135], off offset:-496 nt
; __device__ __forceinline__ bf16_t f2bf1(float f) { return (bf16_t)(cvt_pk_bf16(f, 0.f) & 0xffffu); }
;     __device__ __forceinline__ void operator()(const f32x4 (&acc)[2][2][4][2], const Unit& u, int wr, int wc, int fr, int fq) const {
;     ...
;             for (int ai = 0; ai < 2; ++ai)
; #pragma unroll
;                 for (int m = 0; m < 4; ++m) {
;                     int row = u.pm * BM + ai * HALF + wr * 64 + m * 16 + fr;
;                     asm volatile("" : "+v"(row));
;                     const float rs = R[ai * HALF + wr * 64 + m * 16 + fr];
;                     const int sb = (row - E_MP) >> 6, st = (row - E_MP) & 63, pb = row >> 11, pt = row & 2047;
; #pragma unroll
;                     for (int bj = 0; bj < 2; ++bj) {
;                         const f32x4 v0 = acc[ai][bj][m][0] * rs, v1 = acc[ai][bj][m][1] * rs;
;                         const int c0 = (wc - 2) * 64 + bj * 32 + 8 * fq;
;                         bf16_t* vp = VTG + (size_t)c0 * E_MT + row;
; #pragma unroll
;                         for (int j = 0; j < 4; ++j) { vp[(size_t)j * E_MT] = f2bf1(v0[j]); vp[(size_t)(4 + j) * E_MT] = f2bf1(v1[j]); }
;                         if (is_s) { float* d = ovs + ((size_t)(sb * 128 + 64 + st) * 128 + c0); __builtin_nontemporal_store(v0, (f32x4*)d); __builtin_nontemporal_store(v1, (f32x4*)(d + 4)); }
;                         else if (pt >= 1920) { float* d = ovp + ((size_t)(pb * 128 + (pt - 1920)) * 128 + c0); __builtin_nontemporal_store(v0, (f32x4*)d); __builtin_nontemporal_store(v1, (f32x4*)(d + 4)); }
;                     }
.LBB0_643:
	s_or_b64 exec, exec, s[4:5]
	v_add_u32_e32 v128, 0x80, v170
	s_movk_i32 s0, 0x77f
	v_ashrrev_i32_e32 v129, 31, v128
	v_lshl_add_u64 v[140:141], v[128:129], 1, s[42:43]
	v_ashrrev_i32_e32 v129, 4, v128
	v_and_b32_e32 v130, 0x7ff, v128
	v_and_b32_e32 v129, 0xffffff80, v129
	s_movk_i32 s4, 0xf880
	ds_read_b32 v138, v165 offset:512
	v_and_b32_e32 v132, 63, v128
	v_cmp_lt_u32_e64 s[0:1], s0, v130
	v_add3_u32 v130, v130, v129, s4
	v_lshlrev_b32_e32 v128, 1, v128
	s_movk_i32 s4, 0xff80
	v_and_or_b32 v128, v128, s4, v132
	v_add_u32_e32 v128, 0xffff8040, v128
	v_ashrrev_i32_e32 v129, 31, v128
	v_lshl_add_u64 v[174:175], v[140:141], 0, v[156:157]
	s_mov_b32 s4, 0x24000
	v_lshlrev_b64 v[128:129], 9, v[128:129]
	v_lshl_add_u64 v[172:173], s[30:31], 0, v[128:129]
	s_waitcnt lgkmcnt(0)
	v_pk_mul_f32 v[128:129], v[60:61], v[138:139] op_sel_hi:[1,0]
	s_mov_b32 s4, 0x9000
	v_pk_mul_f32 v[132:133], v[56:57], v[138:139] op_sel_hi:[1,0]
	s_mov_b32 s4, 0x2d000
	s_nop 0
	s_mov_b32 s4, 0x12000
	s_nop 0
	v_ashrrev_i32_e32 v131, 31, v130
	v_lshlrev_b64 v[130:131], 9, v[130:131]
	s_nop 0
	s_mov_b32 s4, 0x36000
	v_lshl_add_u64 v[142:143], s[26:27], 0, v[130:131]
	v_pk_mul_f32 v[130:131], v[62:63], v[138:139] op_sel_hi:[1,0]
	v_pk_mul_f32 v[134:135], v[58:59], v[138:139] op_sel_hi:[1,0]
	s_or_b64 s[0:1], s[38:39], s[0:1]
	s_nop 0
	v_cndmask_b32_e64 v143, v143, v173, s[38:39]
	s_nop 0
	v_cndmask_b32_e64 v142, v142, v172, s[38:39]
	s_nop 0
	v_cvt_pk_bf16_f32 v190, v128, v129
	v_cvt_pk_bf16_f32 v191, v130, v131
	v_cvt_pk_bf16_f32 v217, v132, v133
	v_cvt_pk_bf16_f32 v226, v134, v135
	v_add_co_u32_e32 v174, vcc, v223, v174
	s_nop 1
	v_addc_co_u32_e32 v175, vcc, 0, v175, vcc
	v_mov_b32_dpp v250, v190 quad_perm:[1,0,3,2] row_mask:0xf bank_mask:0xf
	v_perm_b32 v190, v250, v190, v220
	global_store_dword v[174:175], v190, off
	s_mov_b32 s100, 0x12000
	v_lshl_add_u64 v[176:177], v[174:175], 0, s[100:101]
	v_mov_b32_dpp v250, v191 quad_perm:[1,0,3,2] row_mask:0xf bank_mask:0xf
	v_perm_b32 v191, v250, v191, v220
	global_store_dword v[176:177], v191, off
	s_mov_b32 s100, 0x24000
	v_lshl_add_u64 v[176:177], v[174:175], 0, s[100:101]
	v_mov_b32_dpp v250, v217 quad_perm:[1,0,3,2] row_mask:0xf bank_mask:0xf
	v_perm_b32 v217, v250, v217, v220
	global_store_dword v[176:177], v217, off
	s_mov_b32 s100, 0x36000
	v_lshl_add_u64 v[176:177], v[174:175], 0, s[100:101]
	v_mov_b32_dpp v250, v226 quad_perm:[1,0,3,2] row_mask:0xf bank_mask:0xf
	v_perm_b32 v226, v250, v226, v220
	global_store_dword v[176:177], v226, off
	s_and_saveexec_b64 s[4:5], s[0:1]
	s_cbranch_execz .LBB0_645
	v_lshl_add_u64 v[172:173], v[142:143], 0, v[184:185]
	global_store_dwordx4 v[172:173], v[128:131], off offset:-512 nt
	global_store_dwordx4 v[172:173], v[132:135], off offset:-496 nt
.LBB0_645:
	s_or_b64 exec, exec, s[4:5]
	v_mov_b32_e32 v139, v138
	v_mov_b32_e32 v132, v138
	v_mov_b32_e32 v133, v138
	v_pk_mul_f32 v[130:131], v[54:55], v[132:133]
	v_pk_mul_f32 v[128:129], v[52:53], v[138:139]
	v_pk_mul_f32 v[134:135], v[50:51], v[132:133]
	v_pk_mul_f32 v[132:133], v[48:49], v[138:139]
	v_lshl_add_u64 v[138:139], v[140:141], 0, v[158:159]
	s_mov_b32 s4, 0x24000
	s_mov_b32 s4, 0x9000
	s_nop 0
	s_mov_b32 s4, 0x2d000
	s_nop 0
	s_mov_b32 s4, 0x12000
	s_nop 0
	s_mov_b32 s4, 0x36000
	s_nop 0
	s_nop 1
	s_nop 1
	s_nop 0
	v_cvt_pk_bf16_f32 v190, v128, v129
	v_cvt_pk_bf16_f32 v191, v130, v131
	v_cvt_pk_bf16_f32 v217, v132, v133
	v_cvt_pk_bf16_f32 v226, v134, v135
	v_add_co_u32_e32 v138, vcc, v223, v138
	s_nop 1
	v_addc_co_u32_e32 v139, vcc, 0, v139, vcc
	v_mov_b32_dpp v250, v190 quad_perm:[1,0,3,2] row_mask:0xf bank_mask:0xf
	v_perm_b32 v190, v250, v190, v220
	global_store_dword v[138:139], v190, off
	s_mov_b32 s100, 0x12000
	v_lshl_add_u64 v[140:141], v[138:139], 0, s[100:101]
	v_mov_b32_dpp v250, v191 quad_perm:[1,0,3,2] row_mask:0xf bank_mask:0xf
	v_perm_b32 v191, v250, v191, v220
	global_store_dword v[140:141], v191, off
	s_mov_b32 s100, 0x24000
	v_lshl_add_u64 v[140:141], v[138:139], 0, s[100:101]
	v_mov_b32_dpp v250, v217 quad_perm:[1,0,3,2] row_mask:0xf bank_mask:0xf
	v_perm_b32 v217, v250, v217, v220
	global_store_dword v[140:141], v217, off
	s_mov_b32 s100, 0x36000
	v_lshl_add_u64 v[140:141], v[138:139], 0, s[100:101]
	v_mov_b32_dpp v250, v226 quad_perm:[1,0,3,2] row_mask:0xf bank_mask:0xf
	v_perm_b32 v226, v250, v226, v220
	global_store_dword v[140:141], v226, off
	s_and_saveexec_b64 s[4:5], s[0:1]
	s_cbranch_execz .LBB0_647
	v_mov_b32_e32 v137, v185
	v_lshl_add_u64 v[138:139], v[142:143], 0, v[136:137]
	global_store_dwordx4 v[138:139], v[128:131], off offset:-512 nt
	global_store_dwordx4 v[138:139], v[132:135], off offset:-496 nt
; __device__ __forceinline__ bf16_t f2bf1(float f) { return (bf16_t)(cvt_pk_bf16(f, 0.f) & 0xffffu); }
;     __device__ __forceinline__ void operator()(const f32x4 (&acc)[2][2][4][2], const Unit& u, int wr, int wc, int fr, int fq) const {
;     ...
;             for (int ai = 0; ai < 2; ++ai)
; #pragma unroll
;                 for (int m = 0; m < 4; ++m) {
;                     int row = u.pm * BM + ai * HALF + wr * 64 + m * 16 + fr;
;                     asm volatile("" : "+v"(row));
;                     const float rs = R[ai * HALF + wr * 64 + m * 16 + fr];
;                     const int sb = (row - E_MP) >> 6, st = (row - E_MP) & 63, pb = row >> 11, pt = row & 2047;
; #pragma unroll
;                     for (int bj = 0; bj < 2; ++bj) {
;                         const f32x4 v0 = acc[ai][bj][m][0] * rs, v1 = acc[ai][bj][m][1] * rs;
;                         const int c0 = (wc - 2) * 64 + bj * 32 + 8 * fq;
;                         bf16_t* vp = VTG + (size_t)c0 * E_MT + row;
; #pragma unroll
;                         for (int j = 0; j < 4; ++j) { vp[(size_t)j * E_MT] = f2bf1(v0[j]); vp[(size_t)(4 + j) * E_MT] = f2bf1(v1[j]); }
;                         if (is_s) { float* d = ovs + ((size_t)(sb * 128 + 64 + st) * 128 + c0); __builtin_nontemporal_store(v0, (f32x4*)d); __builtin_nontemporal_store(v1, (f32x4*)(d + 4)); }
;                         else if (pt >= 1920) { float* d = ovp + ((size_t)(pb * 128 + (pt - 1920)) * 128 + c0); __builtin_nontemporal_store(v0, (f32x4*)d); __builtin_nontemporal_store(v1, (f32x4*)(d + 4)); }
;                     }
.LBB0_647:
	s_or_b64 exec, exec, s[4:5]
	v_add_u32_e32 v128, 0x90, v170
	s_movk_i32 s0, 0x77f
	v_ashrrev_i32_e32 v129, 31, v128
	v_lshl_add_u64 v[140:141], v[128:129], 1, s[42:43]
	v_ashrrev_i32_e32 v129, 4, v128
	v_and_b32_e32 v130, 0x7ff, v128
	v_and_b32_e32 v129, 0xffffff80, v129
	s_movk_i32 s4, 0xf880
	ds_read_b32 v138, v165 offset:576
	v_and_b32_e32 v132, 63, v128
	v_cmp_lt_u32_e64 s[0:1], s0, v130
	v_add3_u32 v130, v130, v129, s4
	v_lshlrev_b32_e32 v128, 1, v128
	s_movk_i32 s4, 0xff80
	v_and_or_b32 v128, v128, s4, v132
	v_add_u32_e32 v128, 0xffff8040, v128
	v_ashrrev_i32_e32 v129, 31, v128
	v_lshl_add_u64 v[174:175], v[140:141], 0, v[156:157]
	s_mov_b32 s4, 0x24000
	v_lshlrev_b64 v[128:129], 9, v[128:129]
	v_lshl_add_u64 v[172:173], s[30:31], 0, v[128:129]
	s_waitcnt lgkmcnt(0)
	v_pk_mul_f32 v[128:129], v[44:45], v[138:139] op_sel_hi:[1,0]
	s_mov_b32 s4, 0x9000
	v_pk_mul_f32 v[132:133], v[40:41], v[138:139] op_sel_hi:[1,0]
	s_mov_b32 s4, 0x2d000
	s_nop 0
	s_mov_b32 s4, 0x12000
	s_nop 0
	v_ashrrev_i32_e32 v131, 31, v130
	v_lshlrev_b64 v[130:131], 9, v[130:131]
	s_nop 0
	s_mov_b32 s4, 0x36000
	v_lshl_add_u64 v[142:143], s[26:27], 0, v[130:131]
	v_pk_mul_f32 v[130:131], v[46:47], v[138:139] op_sel_hi:[1,0]
	v_pk_mul_f32 v[134:135], v[42:43], v[138:139] op_sel_hi:[1,0]
	s_or_b64 s[0:1], s[38:39], s[0:1]
	s_nop 0
	v_cndmask_b32_e64 v143, v143, v173, s[38:39]
	s_nop 0
	v_cndmask_b32_e64 v142, v142, v172, s[38:39]
	s_nop 0
	v_cvt_pk_bf16_f32 v190, v128, v129
	v_cvt_pk_bf16_f32 v191, v130, v131
	v_cvt_pk_bf16_f32 v217, v132, v133
	v_cvt_pk_bf16_f32 v226, v134, v135
	v_add_co_u32_e32 v174, vcc, v223, v174
	s_nop 1
	v_addc_co_u32_e32 v175, vcc, 0, v175, vcc
	v_mov_b32_dpp v250, v190 quad_perm:[1,0,3,2] row_mask:0xf bank_mask:0xf
	v_perm_b32 v190, v250, v190, v220
	global_store_dword v[174:175], v190, off
	s_mov_b32 s100, 0x12000
	v_lshl_add_u64 v[176:177], v[174:175], 0, s[100:101]
	v_mov_b32_dpp v250, v191 quad_perm:[1,0,3,2] row_mask:0xf bank_mask:0xf
	v_perm_b32 v191, v250, v191, v220
	global_store_dword v[176:177], v191, off
	s_mov_b32 s100, 0x24000
	v_lshl_add_u64 v[176:177], v[174:175], 0, s[100:101]
	v_mov_b32_dpp v250, v217 quad_perm:[1,0,3,2] row_mask:0xf bank_mask:0xf
	v_perm_b32 v217, v250, v217, v220
	global_store_dword v[176:177], v217, off
	s_mov_b32 s100, 0x36000
	v_lshl_add_u64 v[176:177], v[174:175], 0, s[100:101]
	v_mov_b32_dpp v250, v226 quad_perm:[1,0,3,2] row_mask:0xf bank_mask:0xf
	v_perm_b32 v226, v250, v226, v220
	global_store_dword v[176:177], v226, off
	s_and_saveexec_b64 s[4:5], s[0:1]
	s_cbranch_execz .LBB0_649
	v_lshl_add_u64 v[172:173], v[142:143], 0, v[184:185]
	global_store_dwordx4 v[172:173], v[128:131], off offset:-512 nt
	global_store_dwordx4 v[172:173], v[132:135], off offset:-496 nt
.LBB0_649:
	s_or_b64 exec, exec, s[4:5]
	v_mov_b32_e32 v139, v138
	v_mov_b32_e32 v132, v138
	v_mov_b32_e32 v133, v138
	v_pk_mul_f32 v[130:131], v[38:39], v[132:133]
	v_pk_mul_f32 v[128:129], v[36:37], v[138:139]
	v_pk_mul_f32 v[134:135], v[34:35], v[132:133]
	v_pk_mul_f32 v[132:133], v[32:33], v[138:139]
	v_lshl_add_u64 v[138:139], v[140:141], 0, v[158:159]
	s_mov_b32 s4, 0x24000
	s_mov_b32 s4, 0x9000
	s_nop 0
	s_mov_b32 s4, 0x2d000
	s_nop 0
	s_mov_b32 s4, 0x12000
	s_nop 0
	s_mov_b32 s4, 0x36000
	s_nop 0
	s_nop 1
	s_nop 1
	s_nop 0
	v_cvt_pk_bf16_f32 v190, v128, v129
	v_cvt_pk_bf16_f32 v191, v130, v131
	v_cvt_pk_bf16_f32 v217, v132, v133
	v_cvt_pk_bf16_f32 v226, v134, v135
	v_add_co_u32_e32 v138, vcc, v223, v138
	s_nop 1
	v_addc_co_u32_e32 v139, vcc, 0, v139, vcc
	v_mov_b32_dpp v250, v190 quad_perm:[1,0,3,2] row_mask:0xf bank_mask:0xf
	v_perm_b32 v190, v250, v190, v220
	global_store_dword v[138:139], v190, off
	s_mov_b32 s100, 0x12000
	v_lshl_add_u64 v[140:141], v[138:139], 0, s[100:101]
	v_mov_b32_dpp v250, v191 quad_perm:[1,0,3,2] row_mask:0xf bank_mask:0xf
	v_perm_b32 v191, v250, v191, v220
	global_store_dword v[140:141], v191, off
	s_mov_b32 s100, 0x24000
	v_lshl_add_u64 v[140:141], v[138:139], 0, s[100:101]
	v_mov_b32_dpp v250, v217 quad_perm:[1,0,3,2] row_mask:0xf bank_mask:0xf
	v_perm_b32 v217, v250, v217, v220
	global_store_dword v[140:141], v217, off
	s_mov_b32 s100, 0x36000
	v_lshl_add_u64 v[140:141], v[138:139], 0, s[100:101]
	v_mov_b32_dpp v250, v226 quad_perm:[1,0,3,2] row_mask:0xf bank_mask:0xf
	v_perm_b32 v226, v250, v226, v220
	global_store_dword v[140:141], v226, off
	s_and_saveexec_b64 s[4:5], s[0:1]
	s_cbranch_execz .LBB0_651
	v_mov_b32_e32 v137, v185
	v_lshl_add_u64 v[138:139], v[142:143], 0, v[136:137]
	global_store_dwordx4 v[138:139], v[128:131], off offset:-512 nt
	global_store_dwordx4 v[138:139], v[132:135], off offset:-496 nt
; __device__ __forceinline__ bf16_t f2bf1(float f) { return (bf16_t)(cvt_pk_bf16(f, 0.f) & 0xffffu); }
;     __device__ __forceinline__ void operator()(const f32x4 (&acc)[2][2][4][2], const Unit& u, int wr, int wc, int fr, int fq) const {
;     ...
;             for (int ai = 0; ai < 2; ++ai)
; #pragma unroll
;                 for (int m = 0; m < 4; ++m) {
;                     int row = u.pm * BM + ai * HALF + wr * 64 + m * 16 + fr;
;                     asm volatile("" : "+v"(row));
;                     const float rs = R[ai * HALF + wr * 64 + m * 16 + fr];
;                     const int sb = (row - E_MP) >> 6, st = (row - E_MP) & 63, pb = row >> 11, pt = row & 2047;
; #pragma unroll
;                     for (int bj = 0; bj < 2; ++bj) {
;                         const f32x4 v0 = acc[ai][bj][m][0] * rs, v1 = acc[ai][bj][m][1] * rs;
;                         const int c0 = (wc - 2) * 64 + bj * 32 + 8 * fq;
;                         bf16_t* vp = VTG + (size_t)c0 * E_MT + row;
; #pragma unroll
;                         for (int j = 0; j < 4; ++j) { vp[(size_t)j * E_MT] = f2bf1(v0[j]); vp[(size_t)(4 + j) * E_MT] = f2bf1(v1[j]); }
;                         if (is_s) { float* d = ovs + ((size_t)(sb * 128 + 64 + st) * 128 + c0); __builtin_nontemporal_store(v0, (f32x4*)d); __builtin_nontemporal_store(v1, (f32x4*)(d + 4)); }
;                         else if (pt >= 1920) { float* d = ovp + ((size_t)(pb * 128 + (pt - 1920)) * 128 + c0); __builtin_nontemporal_store(v0, (f32x4*)d); __builtin_nontemporal_store(v1, (f32x4*)(d + 4)); }
;                     }
.LBB0_651:
	s_or_b64 exec, exec, s[4:5]
	v_add_u32_e32 v128, 0xa0, v170
	s_movk_i32 s0, 0x77f
	v_ashrrev_i32_e32 v129, 31, v128
	v_lshl_add_u64 v[140:141], v[128:129], 1, s[42:43]
	v_ashrrev_i32_e32 v129, 4, v128
	v_and_b32_e32 v130, 0x7ff, v128
	v_and_b32_e32 v129, 0xffffff80, v129
	s_movk_i32 s4, 0xf880
	ds_read_b32 v138, v165 offset:640
	v_and_b32_e32 v132, 63, v128
	v_cmp_lt_u32_e64 s[0:1], s0, v130
	v_add3_u32 v130, v130, v129, s4
	v_lshlrev_b32_e32 v128, 1, v128
	s_movk_i32 s4, 0xff80
	v_and_or_b32 v128, v128, s4, v132
	v_add_u32_e32 v128, 0xffff8040, v128
	v_ashrrev_i32_e32 v129, 31, v128
	v_lshl_add_u64 v[174:175], v[140:141], 0, v[156:157]
	s_mov_b32 s4, 0x24000
	v_lshlrev_b64 v[128:129], 9, v[128:129]
	v_lshl_add_u64 v[172:173], s[30:31], 0, v[128:129]
	s_waitcnt lgkmcnt(0)
	v_pk_mul_f32 v[128:129], v[28:29], v[138:139] op_sel_hi:[1,0]
	s_mov_b32 s4, 0x9000
	v_pk_mul_f32 v[132:133], v[24:25], v[138:139] op_sel_hi:[1,0]
	s_mov_b32 s4, 0x2d000
	s_nop 0
	s_mov_b32 s4, 0x12000
	s_nop 0
	v_ashrrev_i32_e32 v131, 31, v130
	v_lshlrev_b64 v[130:131], 9, v[130:131]
	s_nop 0
	s_mov_b32 s4, 0x36000
	v_lshl_add_u64 v[142:143], s[26:27], 0, v[130:131]
	v_pk_mul_f32 v[130:131], v[30:31], v[138:139] op_sel_hi:[1,0]
	v_pk_mul_f32 v[134:135], v[26:27], v[138:139] op_sel_hi:[1,0]
	s_or_b64 s[0:1], s[38:39], s[0:1]
	s_nop 0
	v_cndmask_b32_e64 v143, v143, v173, s[38:39]
	s_nop 0
	v_cndmask_b32_e64 v142, v142, v172, s[38:39]
	s_nop 0
	v_cvt_pk_bf16_f32 v190, v128, v129
	v_cvt_pk_bf16_f32 v191, v130, v131
	v_cvt_pk_bf16_f32 v217, v132, v133
	v_cvt_pk_bf16_f32 v226, v134, v135
	v_add_co_u32_e32 v174, vcc, v223, v174
	s_nop 1
	v_addc_co_u32_e32 v175, vcc, 0, v175, vcc
	v_mov_b32_dpp v250, v190 quad_perm:[1,0,3,2] row_mask:0xf bank_mask:0xf
	v_perm_b32 v190, v250, v190, v220
	global_store_dword v[174:175], v190, off
	s_mov_b32 s100, 0x12000
	v_lshl_add_u64 v[176:177], v[174:175], 0, s[100:101]
	v_mov_b32_dpp v250, v191 quad_perm:[1,0,3,2] row_mask:0xf bank_mask:0xf
	v_perm_b32 v191, v250, v191, v220
	global_store_dword v[176:177], v191, off
	s_mov_b32 s100, 0x24000
	v_lshl_add_u64 v[176:177], v[174:175], 0, s[100:101]
	v_mov_b32_dpp v250, v217 quad_perm:[1,0,3,2] row_mask:0xf bank_mask:0xf
	v_perm_b32 v217, v250, v217, v220
	global_store_dword v[176:177], v217, off
	s_mov_b32 s100, 0x36000
	v_lshl_add_u64 v[176:177], v[174:175], 0, s[100:101]
	v_mov_b32_dpp v250, v226 quad_perm:[1,0,3,2] row_mask:0xf bank_mask:0xf
	v_perm_b32 v226, v250, v226, v220
	global_store_dword v[176:177], v226, off
	s_and_saveexec_b64 s[4:5], s[0:1]
	s_cbranch_execz .LBB0_653
	v_lshl_add_u64 v[172:173], v[142:143], 0, v[184:185]
	global_store_dwordx4 v[172:173], v[128:131], off offset:-512 nt
	global_store_dwordx4 v[172:173], v[132:135], off offset:-496 nt
.LBB0_653:
	s_or_b64 exec, exec, s[4:5]
	v_mov_b32_e32 v139, v138
	v_mov_b32_e32 v132, v138
	v_mov_b32_e32 v133, v138
	v_pk_mul_f32 v[130:131], v[22:23], v[132:133]
	v_pk_mul_f32 v[128:129], v[20:21], v[138:139]
	v_pk_mul_f32 v[134:135], v[18:19], v[132:133]
	v_pk_mul_f32 v[132:133], v[16:17], v[138:139]
	v_lshl_add_u64 v[138:139], v[140:141], 0, v[158:159]
	s_mov_b32 s4, 0x24000
	s_mov_b32 s4, 0x9000
	s_nop 0
	s_mov_b32 s4, 0x2d000
	s_nop 0
	s_mov_b32 s4, 0x12000
	s_nop 0
	s_mov_b32 s4, 0x36000
	s_nop 0
	s_nop 1
	s_nop 1
	s_nop 0
	v_cvt_pk_bf16_f32 v190, v128, v129
	v_cvt_pk_bf16_f32 v191, v130, v131
	v_cvt_pk_bf16_f32 v217, v132, v133
	v_cvt_pk_bf16_f32 v226, v134, v135
	v_add_co_u32_e32 v138, vcc, v223, v138
	s_nop 1
	v_addc_co_u32_e32 v139, vcc, 0, v139, vcc
	v_mov_b32_dpp v250, v190 quad_perm:[1,0,3,2] row_mask:0xf bank_mask:0xf
	v_perm_b32 v190, v250, v190, v220
	global_store_dword v[138:139], v190, off
	s_mov_b32 s100, 0x12000
	v_lshl_add_u64 v[140:141], v[138:139], 0, s[100:101]
	v_mov_b32_dpp v250, v191 quad_perm:[1,0,3,2] row_mask:0xf bank_mask:0xf
	v_perm_b32 v191, v250, v191, v220
	global_store_dword v[140:141], v191, off
	s_mov_b32 s100, 0x24000
	v_lshl_add_u64 v[140:141], v[138:139], 0, s[100:101]
	v_mov_b32_dpp v250, v217 quad_perm:[1,0,3,2] row_mask:0xf bank_mask:0xf
	v_perm_b32 v217, v250, v217, v220
	global_store_dword v[140:141], v217, off
	s_mov_b32 s100, 0x36000
	v_lshl_add_u64 v[140:141], v[138:139], 0, s[100:101]
	v_mov_b32_dpp v250, v226 quad_perm:[1,0,3,2] row_mask:0xf bank_mask:0xf
	v_perm_b32 v226, v250, v226, v220
	global_store_dword v[140:141], v226, off
	s_and_saveexec_b64 s[4:5], s[0:1]
	s_cbranch_execz .LBB0_655
	v_mov_b32_e32 v137, v185
	v_lshl_add_u64 v[138:139], v[142:143], 0, v[136:137]
	global_store_dwordx4 v[138:139], v[128:131], off offset:-512 nt
	global_store_dwordx4 v[138:139], v[132:135], off offset:-496 nt
; __device__ __forceinline__ bf16_t f2bf1(float f) { return (bf16_t)(cvt_pk_bf16(f, 0.f) & 0xffffu); }
;     __device__ __forceinline__ void operator()(const f32x4 (&acc)[2][2][4][2], const Unit& u, int wr, int wc, int fr, int fq) const {
;     ...
;             for (int ai = 0; ai < 2; ++ai)
; #pragma unroll
;                 for (int m = 0; m < 4; ++m) {
;                     int row = u.pm * BM + ai * HALF + wr * 64 + m * 16 + fr;
;                     asm volatile("" : "+v"(row));
;                     const float rs = R[ai * HALF + wr * 64 + m * 16 + fr];
;                     const int sb = (row - E_MP) >> 6, st = (row - E_MP) & 63, pb = row >> 11, pt = row & 2047;
; #pragma unroll
;                     for (int bj = 0; bj < 2; ++bj) {
;                         const f32x4 v0 = acc[ai][bj][m][0] * rs, v1 = acc[ai][bj][m][1] * rs;
;                         const int c0 = (wc - 2) * 64 + bj * 32 + 8 * fq;
;                         bf16_t* vp = VTG + (size_t)c0 * E_MT + row;
; #pragma unroll
;                         for (int j = 0; j < 4; ++j) { vp[(size_t)j * E_MT] = f2bf1(v0[j]); vp[(size_t)(4 + j) * E_MT] = f2bf1(v1[j]); }
;                         if (is_s) { float* d = ovs + ((size_t)(sb * 128 + 64 + st) * 128 + c0); __builtin_nontemporal_store(v0, (f32x4*)d); __builtin_nontemporal_store(v1, (f32x4*)(d + 4)); }
;                         else if (pt >= 1920) { float* d = ovp + ((size_t)(pb * 128 + (pt - 1920)) * 128 + c0); __builtin_nontemporal_store(v0, (f32x4*)d); __builtin_nontemporal_store(v1, (f32x4*)(d + 4)); }
;                     }
.LBB0_655:
	s_or_b64 exec, exec, s[4:5]
	v_add_u32_e32 v128, 0xb0, v170
	s_movk_i32 s0, 0x77f
	v_ashrrev_i32_e32 v129, 31, v128
	v_lshl_add_u64 v[140:141], v[128:129], 1, s[42:43]
	v_ashrrev_i32_e32 v129, 4, v128
	v_and_b32_e32 v130, 0x7ff, v128
	v_and_b32_e32 v129, 0xffffff80, v129
	s_movk_i32 s4, 0xf880
	ds_read_b32 v138, v165 offset:704
	v_and_b32_e32 v132, 63, v128
	v_cmp_lt_u32_e64 s[0:1], s0, v130
	v_add3_u32 v130, v130, v129, s4
	v_lshlrev_b32_e32 v128, 1, v128
	s_movk_i32 s4, 0xff80
	v_and_or_b32 v128, v128, s4, v132
	v_add_u32_e32 v128, 0xffff8040, v128
	v_ashrrev_i32_e32 v129, 31, v128
	v_lshl_add_u64 v[172:173], v[140:141], 0, v[156:157]
	s_mov_b32 s4, 0x24000
	v_lshlrev_b64 v[128:129], 9, v[128:129]
	v_lshl_add_u64 v[170:171], s[30:31], 0, v[128:129]
	s_waitcnt lgkmcnt(0)
	v_pk_mul_f32 v[128:129], v[12:13], v[138:139] op_sel_hi:[1,0]
	s_mov_b32 s4, 0x9000
	v_pk_mul_f32 v[132:133], v[8:9], v[138:139] op_sel_hi:[1,0]
	s_mov_b32 s4, 0x2d000
	s_nop 0
	s_mov_b32 s4, 0x12000
	s_nop 0
	v_ashrrev_i32_e32 v131, 31, v130
	v_lshlrev_b64 v[130:131], 9, v[130:131]
	s_nop 0
	s_mov_b32 s4, 0x36000
	v_lshl_add_u64 v[142:143], s[26:27], 0, v[130:131]
	v_pk_mul_f32 v[130:131], v[14:15], v[138:139] op_sel_hi:[1,0]
	v_pk_mul_f32 v[134:135], v[10:11], v[138:139] op_sel_hi:[1,0]
	s_or_b64 s[0:1], s[38:39], s[0:1]
	s_nop 0
	v_cndmask_b32_e64 v143, v143, v171, s[38:39]
	s_nop 0
	v_cndmask_b32_e64 v142, v142, v170, s[38:39]
	s_nop 0
	v_cvt_pk_bf16_f32 v190, v128, v129
	v_cvt_pk_bf16_f32 v191, v130, v131
	v_cvt_pk_bf16_f32 v217, v132, v133
	v_cvt_pk_bf16_f32 v226, v134, v135
	v_add_co_u32_e32 v172, vcc, v223, v172
	s_nop 1
	v_addc_co_u32_e32 v173, vcc, 0, v173, vcc
	v_mov_b32_dpp v250, v190 quad_perm:[1,0,3,2] row_mask:0xf bank_mask:0xf
	v_perm_b32 v190, v250, v190, v220
	global_store_dword v[172:173], v190, off
	s_mov_b32 s100, 0x12000
	v_lshl_add_u64 v[174:175], v[172:173], 0, s[100:101]
	v_mov_b32_dpp v250, v191 quad_perm:[1,0,3,2] row_mask:0xf bank_mask:0xf
	v_perm_b32 v191, v250, v191, v220
	global_store_dword v[174:175], v191, off
	s_mov_b32 s100, 0x24000
	v_lshl_add_u64 v[174:175], v[172:173], 0, s[100:101]
	v_mov_b32_dpp v250, v217 quad_perm:[1,0,3,2] row_mask:0xf bank_mask:0xf
	v_perm_b32 v217, v250, v217, v220
	global_store_dword v[174:175], v217, off
	s_mov_b32 s100, 0x36000
	v_lshl_add_u64 v[174:175], v[172:173], 0, s[100:101]
	v_mov_b32_dpp v250, v226 quad_perm:[1,0,3,2] row_mask:0xf bank_mask:0xf
	v_perm_b32 v226, v250, v226, v220
	global_store_dword v[174:175], v226, off
	s_and_saveexec_b64 s[4:5], s[0:1]
	s_cbranch_execz .LBB0_657
	v_lshl_add_u64 v[170:171], v[142:143], 0, v[184:185]
	global_store_dwordx4 v[170:171], v[128:131], off offset:-512 nt
	global_store_dwordx4 v[170:171], v[132:135], off offset:-496 nt
.LBB0_657:
	s_or_b64 exec, exec, s[4:5]
	v_mov_b32_e32 v139, v138
	v_mov_b32_e32 v132, v138
	v_mov_b32_e32 v133, v138
	v_pk_mul_f32 v[130:131], v[6:7], v[132:133]
	v_pk_mul_f32 v[128:129], v[4:5], v[138:139]
	v_pk_mul_f32 v[134:135], v[2:3], v[132:133]
	v_pk_mul_f32 v[132:133], v[0:1], v[138:139]
	v_lshl_add_u64 v[138:139], v[140:141], 0, v[158:159]
	s_mov_b32 s4, 0x24000
	s_mov_b32 s4, 0x9000
	s_nop 0
	s_mov_b32 s4, 0x2d000
	s_nop 0
	s_mov_b32 s4, 0x12000
	s_nop 0
	s_mov_b32 s4, 0x36000
	s_nop 0
	s_nop 1
	s_nop 1
	s_nop 0
	v_cvt_pk_bf16_f32 v190, v128, v129
	v_cvt_pk_bf16_f32 v191, v130, v131
	v_cvt_pk_bf16_f32 v217, v132, v133
	v_cvt_pk_bf16_f32 v226, v134, v135
	v_add_co_u32_e32 v138, vcc, v223, v138
	s_nop 1
	v_addc_co_u32_e32 v139, vcc, 0, v139, vcc
	v_mov_b32_dpp v250, v190 quad_perm:[1,0,3,2] row_mask:0xf bank_mask:0xf
	v_perm_b32 v190, v250, v190, v220
	global_store_dword v[138:139], v190, off
	s_mov_b32 s100, 0x12000
	v_lshl_add_u64 v[140:141], v[138:139], 0, s[100:101]
	v_mov_b32_dpp v250, v191 quad_perm:[1,0,3,2] row_mask:0xf bank_mask:0xf
	v_perm_b32 v191, v250, v191, v220
	global_store_dword v[140:141], v191, off
	s_mov_b32 s100, 0x24000
	v_lshl_add_u64 v[140:141], v[138:139], 0, s[100:101]
	v_mov_b32_dpp v250, v217 quad_perm:[1,0,3,2] row_mask:0xf bank_mask:0xf
	v_perm_b32 v217, v250, v217, v220
	global_store_dword v[140:141], v217, off
	s_mov_b32 s100, 0x36000
	v_lshl_add_u64 v[140:141], v[138:139], 0, s[100:101]
	v_mov_b32_dpp v250, v226 quad_perm:[1,0,3,2] row_mask:0xf bank_mask:0xf
	v_perm_b32 v226, v250, v226, v220
	global_store_dword v[140:141], v226, off
	s_and_saveexec_b64 s[4:5], s[0:1]
	s_cbranch_execz .LBB0_659
	v_mov_b32_e32 v137, v185
	v_lshl_add_u64 v[136:137], v[142:143], 0, v[136:137]
	global_store_dwordx4 v[136:137], v[128:131], off offset:-512 nt
	global_store_dwordx4 v[136:137], v[132:135], off offset:-496 nt
